# FFN-up epilogue fast path: packed f32 mul/add for the SiLU gate's scale and +1 steps (12 VALU instead of 16 per row pair)
# baseline (speedup 1.0000x reference)
.Lffnepi0_fast:
	s_mov_b32 s52, 0xbfb8aa3b
	v_add_u32_e32 v236, 15, v184
	v_cmp_lt_i32_e64 s[4:5], v236, v170
	v_mov_b32_e32 v235, v183
	ds_read2_b64 v[192:195], v235 offset0:0 offset1:16
	ds_read2_b64 v[198:201], v235 offset0:64 offset1:80
	ds_read2_b64 v[204:207], v235 offset0:128 offset1:144
	ds_read2_b64 v[208:211], v235 offset0:192 offset1:208
	v_add_u32_e32 v235, 0x800, v235
	ds_read2_b64 v[212:215], v235 offset0:0 offset1:16
	s_waitcnt lgkmcnt(3)
	v_pk_fma_f32 v[128:129], v[142:143], v[156:157], v[140:141]
	v_pk_fma_f32 v[228:229], v[142:143], v[192:193], v[140:141]
	v_pk_fma_f32 v[224:225], v[148:149], v[130:131], v[152:153]
	v_pk_fma_f32 v[230:231], v[148:149], v[194:195], v[152:153]
	v_pk_fma_f32 v[128:129], v[138:139], v[158:159], v[128:129]
	v_pk_fma_f32 v[228:229], v[138:139], v[156:157], v[228:229]
	v_pk_fma_f32 v[224:225], v[146:147], v[160:161], v[224:225]
	v_pk_fma_f32 v[230:231], v[146:147], v[130:131], v[230:231]
	v_pk_fma_f32 v[128:129], v[144:145], v[192:193], v[128:129]
	v_pk_fma_f32 v[228:229], v[144:145], v[198:199], v[228:229]
	v_pk_fma_f32 v[224:225], v[150:151], v[194:195], v[224:225]
	v_pk_fma_f32 v[230:231], v[150:151], v[200:201], v[230:231]
	v_pk_mul_f32 v[226:227], v[128:129], s[52:53] op_sel_hi:[1,0]
	v_pk_mul_f32 v[232:233], v[228:229], s[52:53] op_sel_hi:[1,0]
	v_exp_f32_e32 v226, v226
	v_exp_f32_e32 v232, v232
	v_exp_f32_e32 v227, v227
	v_exp_f32_e32 v233, v233
	v_pk_add_f32 v[226:227], v[226:227], 1.0 op_sel_hi:[1,0]
	v_pk_add_f32 v[232:233], v[232:233], 1.0 op_sel_hi:[1,0]
	v_rcp_f32_e32 v226, v226
	v_rcp_f32_e32 v232, v232
	v_rcp_f32_e32 v227, v227
	v_rcp_f32_e32 v233, v233
	v_pk_mul_f32 v[128:129], v[128:129], v[226:227]
	v_pk_mul_f32 v[228:229], v[228:229], v[232:233]
	v_pk_mul_f32 v[128:129], v[224:225], v[128:129]
	v_pk_mul_f32 v[228:229], v[230:231], v[228:229]
	v_cvt_pk_bf16_f32 v128, v128, v129
	v_cvt_pk_bf16_f32 v228, v228, v229
	global_store_dword v[154:155], v128, off
	v_lshl_add_u64 v[154:155], v[154:155], 0, s[38:39]
	global_store_dword v[154:155], v228, off
	v_lshl_add_u64 v[154:155], v[154:155], 0, s[38:39]
	ds_read2_b64 v[216:219], v235 offset0:64 offset1:80
	ds_read2_b64 v[220:223], v235 offset0:128 offset1:144
	s_waitcnt lgkmcnt(3)
	v_pk_fma_f32 v[128:129], v[142:143], v[198:199], v[140:141]
	v_pk_fma_f32 v[228:229], v[142:143], v[204:205], v[140:141]
	v_pk_fma_f32 v[224:225], v[148:149], v[200:201], v[152:153]
	v_pk_fma_f32 v[230:231], v[148:149], v[206:207], v[152:153]
	v_pk_fma_f32 v[128:129], v[138:139], v[192:193], v[128:129]
	v_pk_fma_f32 v[228:229], v[138:139], v[198:199], v[228:229]
	v_pk_fma_f32 v[224:225], v[146:147], v[194:195], v[224:225]
	v_pk_fma_f32 v[230:231], v[146:147], v[200:201], v[230:231]
	v_pk_fma_f32 v[128:129], v[144:145], v[204:205], v[128:129]
	v_pk_fma_f32 v[228:229], v[144:145], v[208:209], v[228:229]
	v_pk_fma_f32 v[224:225], v[150:151], v[206:207], v[224:225]
	v_pk_fma_f32 v[230:231], v[150:151], v[210:211], v[230:231]
	v_pk_mul_f32 v[226:227], v[128:129], s[52:53] op_sel_hi:[1,0]
	v_pk_mul_f32 v[232:233], v[228:229], s[52:53] op_sel_hi:[1,0]
	v_exp_f32_e32 v226, v226
	v_exp_f32_e32 v232, v232
	v_exp_f32_e32 v227, v227
	v_exp_f32_e32 v233, v233
	v_pk_add_f32 v[226:227], v[226:227], 1.0 op_sel_hi:[1,0]
	v_pk_add_f32 v[232:233], v[232:233], 1.0 op_sel_hi:[1,0]
	v_rcp_f32_e32 v226, v226
	v_rcp_f32_e32 v232, v232
	v_rcp_f32_e32 v227, v227
	v_rcp_f32_e32 v233, v233
	v_pk_mul_f32 v[128:129], v[128:129], v[226:227]
	v_pk_mul_f32 v[228:229], v[228:229], v[232:233]
	v_pk_mul_f32 v[128:129], v[224:225], v[128:129]
	v_pk_mul_f32 v[228:229], v[230:231], v[228:229]
	v_cvt_pk_bf16_f32 v128, v128, v129
	v_cvt_pk_bf16_f32 v228, v228, v229
	global_store_dword v[154:155], v128, off
	v_lshl_add_u64 v[154:155], v[154:155], 0, s[38:39]
	global_store_dword v[154:155], v228, off
	v_lshl_add_u64 v[154:155], v[154:155], 0, s[38:39]
	ds_read2_b64 v[186:189], v235 offset0:192 offset1:208
	v_add_u32_e32 v235, 0x800, v235
	ds_read2_b64 v[192:195], v235 offset0:0 offset1:16
	s_waitcnt lgkmcnt(3)
	v_pk_fma_f32 v[128:129], v[142:143], v[208:209], v[140:141]
	v_pk_fma_f32 v[228:229], v[142:143], v[212:213], v[140:141]
	v_pk_fma_f32 v[224:225], v[148:149], v[210:211], v[152:153]
	v_pk_fma_f32 v[230:231], v[148:149], v[214:215], v[152:153]
	v_pk_fma_f32 v[128:129], v[138:139], v[204:205], v[128:129]
	v_pk_fma_f32 v[228:229], v[138:139], v[208:209], v[228:229]
	v_pk_fma_f32 v[224:225], v[146:147], v[206:207], v[224:225]
	v_pk_fma_f32 v[230:231], v[146:147], v[210:211], v[230:231]
	v_pk_fma_f32 v[128:129], v[144:145], v[212:213], v[128:129]
	v_pk_fma_f32 v[228:229], v[144:145], v[216:217], v[228:229]
	v_pk_fma_f32 v[224:225], v[150:151], v[214:215], v[224:225]
	v_pk_fma_f32 v[230:231], v[150:151], v[218:219], v[230:231]
	v_pk_mul_f32 v[226:227], v[128:129], s[52:53] op_sel_hi:[1,0]
	v_pk_mul_f32 v[232:233], v[228:229], s[52:53] op_sel_hi:[1,0]
	v_exp_f32_e32 v226, v226
	v_exp_f32_e32 v232, v232
	v_exp_f32_e32 v227, v227
	v_exp_f32_e32 v233, v233
	v_pk_add_f32 v[226:227], v[226:227], 1.0 op_sel_hi:[1,0]
	v_pk_add_f32 v[232:233], v[232:233], 1.0 op_sel_hi:[1,0]
	v_rcp_f32_e32 v226, v226
	v_rcp_f32_e32 v232, v232
	v_rcp_f32_e32 v227, v227
	v_rcp_f32_e32 v233, v233
	v_pk_mul_f32 v[128:129], v[128:129], v[226:227]
	v_pk_mul_f32 v[228:229], v[228:229], v[232:233]
	v_pk_mul_f32 v[128:129], v[224:225], v[128:129]
	v_pk_mul_f32 v[228:229], v[230:231], v[228:229]
	v_cvt_pk_bf16_f32 v128, v128, v129
	v_cvt_pk_bf16_f32 v228, v228, v229
	global_store_dword v[154:155], v128, off
	v_lshl_add_u64 v[154:155], v[154:155], 0, s[38:39]
	global_store_dword v[154:155], v228, off
	v_lshl_add_u64 v[154:155], v[154:155], 0, s[38:39]
	ds_read2_b64 v[198:201], v235 offset0:64 offset1:80
	ds_read2_b64 v[204:207], v235 offset0:128 offset1:144
	s_waitcnt lgkmcnt(3)
	v_pk_fma_f32 v[128:129], v[142:143], v[216:217], v[140:141]
	v_pk_fma_f32 v[228:229], v[142:143], v[220:221], v[140:141]
	v_pk_fma_f32 v[224:225], v[148:149], v[218:219], v[152:153]
	v_pk_fma_f32 v[230:231], v[148:149], v[222:223], v[152:153]
	v_pk_fma_f32 v[128:129], v[138:139], v[212:213], v[128:129]
	v_pk_fma_f32 v[228:229], v[138:139], v[216:217], v[228:229]
	v_pk_fma_f32 v[224:225], v[146:147], v[214:215], v[224:225]
	v_pk_fma_f32 v[230:231], v[146:147], v[218:219], v[230:231]
	v_pk_fma_f32 v[128:129], v[144:145], v[220:221], v[128:129]
	v_pk_fma_f32 v[228:229], v[144:145], v[186:187], v[228:229]
	v_pk_fma_f32 v[224:225], v[150:151], v[222:223], v[224:225]
	v_pk_fma_f32 v[230:231], v[150:151], v[188:189], v[230:231]
	v_pk_mul_f32 v[226:227], v[128:129], s[52:53] op_sel_hi:[1,0]
	v_pk_mul_f32 v[232:233], v[228:229], s[52:53] op_sel_hi:[1,0]
	v_exp_f32_e32 v226, v226
	v_exp_f32_e32 v232, v232
	v_exp_f32_e32 v227, v227
	v_exp_f32_e32 v233, v233
	v_pk_add_f32 v[226:227], v[226:227], 1.0 op_sel_hi:[1,0]
	v_pk_add_f32 v[232:233], v[232:233], 1.0 op_sel_hi:[1,0]
	v_rcp_f32_e32 v226, v226
	v_rcp_f32_e32 v232, v232
	v_rcp_f32_e32 v227, v227
	v_rcp_f32_e32 v233, v233
	v_pk_mul_f32 v[128:129], v[128:129], v[226:227]
	v_pk_mul_f32 v[228:229], v[228:229], v[232:233]
	v_pk_mul_f32 v[128:129], v[224:225], v[128:129]
	v_pk_mul_f32 v[228:229], v[230:231], v[228:229]
	v_cvt_pk_bf16_f32 v128, v128, v129
	v_cvt_pk_bf16_f32 v228, v228, v229
	global_store_dword v[154:155], v128, off
	v_lshl_add_u64 v[154:155], v[154:155], 0, s[38:39]
	global_store_dword v[154:155], v228, off
	v_lshl_add_u64 v[154:155], v[154:155], 0, s[38:39]
	ds_read2_b64 v[208:211], v235 offset0:192 offset1:208
	v_add_u32_e32 v235, 0x800, v235
	ds_read2_b64 v[212:215], v235 offset0:0 offset1:16
	s_waitcnt lgkmcnt(3)
	v_pk_fma_f32 v[128:129], v[142:143], v[186:187], v[140:141]
	v_pk_fma_f32 v[228:229], v[142:143], v[192:193], v[140:141]
	v_pk_fma_f32 v[224:225], v[148:149], v[188:189], v[152:153]
	v_pk_fma_f32 v[230:231], v[148:149], v[194:195], v[152:153]
	v_pk_fma_f32 v[128:129], v[138:139], v[220:221], v[128:129]
	v_pk_fma_f32 v[228:229], v[138:139], v[186:187], v[228:229]
	v_pk_fma_f32 v[224:225], v[146:147], v[222:223], v[224:225]
	v_pk_fma_f32 v[230:231], v[146:147], v[188:189], v[230:231]
	v_pk_fma_f32 v[128:129], v[144:145], v[192:193], v[128:129]
	v_pk_fma_f32 v[228:229], v[144:145], v[198:199], v[228:229]
	v_pk_fma_f32 v[224:225], v[150:151], v[194:195], v[224:225]
	v_pk_fma_f32 v[230:231], v[150:151], v[200:201], v[230:231]
	v_pk_mul_f32 v[226:227], v[128:129], s[52:53] op_sel_hi:[1,0]
	v_pk_mul_f32 v[232:233], v[228:229], s[52:53] op_sel_hi:[1,0]
	v_exp_f32_e32 v226, v226
	v_exp_f32_e32 v232, v232
	v_exp_f32_e32 v227, v227
	v_exp_f32_e32 v233, v233
	v_pk_add_f32 v[226:227], v[226:227], 1.0 op_sel_hi:[1,0]
	v_pk_add_f32 v[232:233], v[232:233], 1.0 op_sel_hi:[1,0]
	v_rcp_f32_e32 v226, v226
	v_rcp_f32_e32 v232, v232
	v_rcp_f32_e32 v227, v227
	v_rcp_f32_e32 v233, v233
	v_pk_mul_f32 v[128:129], v[128:129], v[226:227]
	v_pk_mul_f32 v[228:229], v[228:229], v[232:233]
	v_pk_mul_f32 v[128:129], v[224:225], v[128:129]
	v_pk_mul_f32 v[228:229], v[230:231], v[228:229]
	v_cvt_pk_bf16_f32 v128, v128, v129
	v_cvt_pk_bf16_f32 v228, v228, v229
	global_store_dword v[154:155], v128, off
	v_lshl_add_u64 v[154:155], v[154:155], 0, s[38:39]
	global_store_dword v[154:155], v228, off
	v_lshl_add_u64 v[154:155], v[154:155], 0, s[38:39]
	ds_read2_b64 v[216:219], v235 offset0:64 offset1:80
	ds_read2_b64 v[220:223], v235 offset0:128 offset1:144
	s_waitcnt lgkmcnt(3)
	v_pk_fma_f32 v[128:129], v[142:143], v[198:199], v[140:141]
	v_pk_fma_f32 v[228:229], v[142:143], v[204:205], v[140:141]
	v_pk_fma_f32 v[224:225], v[148:149], v[200:201], v[152:153]
	v_pk_fma_f32 v[230:231], v[148:149], v[206:207], v[152:153]
	v_pk_fma_f32 v[128:129], v[138:139], v[192:193], v[128:129]
	v_pk_fma_f32 v[228:229], v[138:139], v[198:199], v[228:229]
	v_pk_fma_f32 v[224:225], v[146:147], v[194:195], v[224:225]
	v_pk_fma_f32 v[230:231], v[146:147], v[200:201], v[230:231]
	v_pk_fma_f32 v[128:129], v[144:145], v[204:205], v[128:129]
	v_pk_fma_f32 v[228:229], v[144:145], v[208:209], v[228:229]
	v_pk_fma_f32 v[224:225], v[150:151], v[206:207], v[224:225]
	v_pk_fma_f32 v[230:231], v[150:151], v[210:211], v[230:231]
	v_pk_mul_f32 v[226:227], v[128:129], s[52:53] op_sel_hi:[1,0]
	v_pk_mul_f32 v[232:233], v[228:229], s[52:53] op_sel_hi:[1,0]
	v_exp_f32_e32 v226, v226
	v_exp_f32_e32 v232, v232
	v_exp_f32_e32 v227, v227
	v_exp_f32_e32 v233, v233
	v_pk_add_f32 v[226:227], v[226:227], 1.0 op_sel_hi:[1,0]
	v_pk_add_f32 v[232:233], v[232:233], 1.0 op_sel_hi:[1,0]
	v_rcp_f32_e32 v226, v226
	v_rcp_f32_e32 v232, v232
	v_rcp_f32_e32 v227, v227
	v_rcp_f32_e32 v233, v233
	v_pk_mul_f32 v[128:129], v[128:129], v[226:227]
	v_pk_mul_f32 v[228:229], v[228:229], v[232:233]
	v_pk_mul_f32 v[128:129], v[224:225], v[128:129]
	v_pk_mul_f32 v[228:229], v[230:231], v[228:229]
	v_cvt_pk_bf16_f32 v128, v128, v129
	v_cvt_pk_bf16_f32 v228, v228, v229
	global_store_dword v[154:155], v128, off
	v_lshl_add_u64 v[154:155], v[154:155], 0, s[38:39]
	global_store_dword v[154:155], v228, off
	v_lshl_add_u64 v[154:155], v[154:155], 0, s[38:39]
	ds_read2_b64 v[186:189], v235 offset0:192 offset1:208
	s_waitcnt lgkmcnt(2)
	v_pk_fma_f32 v[128:129], v[142:143], v[208:209], v[140:141]
	v_pk_fma_f32 v[228:229], v[142:143], v[212:213], v[140:141]
	v_pk_fma_f32 v[224:225], v[148:149], v[210:211], v[152:153]
	v_pk_fma_f32 v[230:231], v[148:149], v[214:215], v[152:153]
	v_pk_fma_f32 v[128:129], v[138:139], v[204:205], v[128:129]
	v_pk_fma_f32 v[228:229], v[138:139], v[208:209], v[228:229]
	v_pk_fma_f32 v[224:225], v[146:147], v[206:207], v[224:225]
	v_pk_fma_f32 v[230:231], v[146:147], v[210:211], v[230:231]
	v_pk_fma_f32 v[128:129], v[144:145], v[212:213], v[128:129]
	v_pk_fma_f32 v[228:229], v[144:145], v[216:217], v[228:229]
	v_pk_fma_f32 v[224:225], v[150:151], v[214:215], v[224:225]
	v_pk_fma_f32 v[230:231], v[150:151], v[218:219], v[230:231]
	v_pk_mul_f32 v[226:227], v[128:129], s[52:53] op_sel_hi:[1,0]
	v_pk_mul_f32 v[232:233], v[228:229], s[52:53] op_sel_hi:[1,0]
	v_exp_f32_e32 v226, v226
	v_exp_f32_e32 v232, v232
	v_exp_f32_e32 v227, v227
	v_exp_f32_e32 v233, v233
	v_pk_add_f32 v[226:227], v[226:227], 1.0 op_sel_hi:[1,0]
	v_pk_add_f32 v[232:233], v[232:233], 1.0 op_sel_hi:[1,0]
	v_rcp_f32_e32 v226, v226
	v_rcp_f32_e32 v232, v232
	v_rcp_f32_e32 v227, v227
	v_rcp_f32_e32 v233, v233
	v_pk_mul_f32 v[128:129], v[128:129], v[226:227]
	v_pk_mul_f32 v[228:229], v[228:229], v[232:233]
	v_pk_mul_f32 v[128:129], v[224:225], v[128:129]
	v_pk_mul_f32 v[228:229], v[230:231], v[228:229]
	v_cvt_pk_bf16_f32 v128, v128, v129
	v_cvt_pk_bf16_f32 v228, v228, v229
	global_store_dword v[154:155], v128, off
	v_lshl_add_u64 v[154:155], v[154:155], 0, s[38:39]
	global_store_dword v[154:155], v228, off
	v_lshl_add_u64 v[154:155], v[154:155], 0, s[38:39]
	s_waitcnt lgkmcnt(0)
	v_pk_fma_f32 v[128:129], v[142:143], v[216:217], v[140:141]
	v_pk_fma_f32 v[228:229], v[142:143], v[220:221], v[140:141]
	v_pk_fma_f32 v[224:225], v[148:149], v[218:219], v[152:153]
	v_pk_fma_f32 v[230:231], v[148:149], v[222:223], v[152:153]
	v_pk_fma_f32 v[128:129], v[138:139], v[212:213], v[128:129]
	v_pk_fma_f32 v[228:229], v[138:139], v[216:217], v[228:229]
	v_pk_fma_f32 v[224:225], v[146:147], v[214:215], v[224:225]
	v_pk_fma_f32 v[230:231], v[146:147], v[218:219], v[230:231]
	v_pk_fma_f32 v[128:129], v[144:145], v[220:221], v[128:129]
	v_pk_fma_f32 v[228:229], v[144:145], v[186:187], v[228:229]
	v_pk_fma_f32 v[224:225], v[150:151], v[222:223], v[224:225]
	v_pk_fma_f32 v[230:231], v[150:151], v[188:189], v[230:231]
	v_pk_mul_f32 v[226:227], v[128:129], s[52:53] op_sel_hi:[1,0]
	v_pk_mul_f32 v[232:233], v[228:229], s[52:53] op_sel_hi:[1,0]
	v_exp_f32_e32 v226, v226
	v_exp_f32_e32 v232, v232
	v_exp_f32_e32 v227, v227
	v_exp_f32_e32 v233, v233
	v_pk_add_f32 v[226:227], v[226:227], 1.0 op_sel_hi:[1,0]
	v_pk_add_f32 v[232:233], v[232:233], 1.0 op_sel_hi:[1,0]
	v_rcp_f32_e32 v226, v226
	v_rcp_f32_e32 v232, v232
	v_rcp_f32_e32 v227, v227
	v_rcp_f32_e32 v233, v233
	v_pk_mul_f32 v[128:129], v[128:129], v[226:227]
	v_pk_mul_f32 v[228:229], v[228:229], v[232:233]
	v_pk_mul_f32 v[128:129], v[224:225], v[128:129]
	v_pk_mul_f32 v[228:229], v[230:231], v[228:229]
	v_cvt_pk_bf16_f32 v128, v128, v129
	v_cvt_pk_bf16_f32 v228, v228, v229
	global_store_dword v[154:155], v128, off
	v_lshl_add_u64 v[154:155], v[154:155], 0, s[38:39]
	s_and_saveexec_b64 s[40:41], s[4:5]
	global_store_dword v[154:155], v228, off
	s_or_b64 exec, exec, s[40:41]
	s_branch .LBB0_1080

.Lffnepi1_fast:
	s_mov_b32 s52, 0xbfb8aa3b
	v_add_u32_e32 v118, 15, v30
	v_cmp_lt_i32_e32 vcc, v118, v170
	v_mov_b32_e32 v117, v29
	ds_read2_b64 v[56:59], v117 offset0:0 offset1:16
	ds_read2_b64 v[60:63], v117 offset0:64 offset1:80
	ds_read2_b64 v[64:67], v117 offset0:128 offset1:144
	ds_read2_b64 v[68:71], v117 offset0:192 offset1:208
	v_add_u32_e32 v117, 0x800, v117
	ds_read2_b64 v[72:75], v117 offset0:0 offset1:16
	s_waitcnt lgkmcnt(3)
	v_pk_fma_f32 v[36:37], v[8:9], v[22:23], v[6:7]
	v_pk_fma_f32 v[110:111], v[8:9], v[56:57], v[6:7]
	v_pk_fma_f32 v[106:107], v[14:15], v[2:3], v[18:19]
	v_pk_fma_f32 v[112:113], v[14:15], v[58:59], v[18:19]
	v_pk_fma_f32 v[36:37], v[4:5], v[24:25], v[36:37]
	v_pk_fma_f32 v[110:111], v[4:5], v[22:23], v[110:111]
	v_pk_fma_f32 v[106:107], v[12:13], v[26:27], v[106:107]
	v_pk_fma_f32 v[112:113], v[12:13], v[2:3], v[112:113]
	v_pk_fma_f32 v[36:37], v[10:11], v[56:57], v[36:37]
	v_pk_fma_f32 v[110:111], v[10:11], v[60:61], v[110:111]
	v_pk_fma_f32 v[106:107], v[16:17], v[58:59], v[106:107]
	v_pk_fma_f32 v[112:113], v[16:17], v[62:63], v[112:113]
	v_pk_mul_f32 v[108:109], v[36:37], s[52:53] op_sel_hi:[1,0]
	v_pk_mul_f32 v[114:115], v[110:111], s[52:53] op_sel_hi:[1,0]
	v_exp_f32_e32 v108, v108
	v_exp_f32_e32 v114, v114
	v_exp_f32_e32 v109, v109
	v_exp_f32_e32 v115, v115
	v_pk_add_f32 v[108:109], v[108:109], 1.0 op_sel_hi:[1,0]
	v_pk_add_f32 v[114:115], v[114:115], 1.0 op_sel_hi:[1,0]
	v_rcp_f32_e32 v108, v108
	v_rcp_f32_e32 v114, v114
	v_rcp_f32_e32 v109, v109
	v_rcp_f32_e32 v115, v115
	v_pk_mul_f32 v[36:37], v[36:37], v[108:109]
	v_pk_mul_f32 v[110:111], v[110:111], v[114:115]
	v_pk_mul_f32 v[36:37], v[106:107], v[36:37]
	v_pk_mul_f32 v[110:111], v[112:113], v[110:111]
	v_cvt_pk_bf16_f32 v36, v36, v37
	v_cvt_pk_bf16_f32 v110, v110, v111
	global_store_dword v[20:21], v36, off
	v_lshl_add_u64 v[20:21], v[20:21], 0, s[38:39]
	global_store_dword v[20:21], v110, off
	v_lshl_add_u64 v[20:21], v[20:21], 0, s[38:39]
	ds_read2_b64 v[76:79], v117 offset0:64 offset1:80
	ds_read2_b64 v[102:105], v117 offset0:128 offset1:144
	s_waitcnt lgkmcnt(3)
	v_pk_fma_f32 v[36:37], v[8:9], v[60:61], v[6:7]
	v_pk_fma_f32 v[110:111], v[8:9], v[64:65], v[6:7]
	v_pk_fma_f32 v[106:107], v[14:15], v[62:63], v[18:19]
	v_pk_fma_f32 v[112:113], v[14:15], v[66:67], v[18:19]
	v_pk_fma_f32 v[36:37], v[4:5], v[56:57], v[36:37]
	v_pk_fma_f32 v[110:111], v[4:5], v[60:61], v[110:111]
	v_pk_fma_f32 v[106:107], v[12:13], v[58:59], v[106:107]
	v_pk_fma_f32 v[112:113], v[12:13], v[62:63], v[112:113]
	v_pk_fma_f32 v[36:37], v[10:11], v[64:65], v[36:37]
	v_pk_fma_f32 v[110:111], v[10:11], v[68:69], v[110:111]
	v_pk_fma_f32 v[106:107], v[16:17], v[66:67], v[106:107]
	v_pk_fma_f32 v[112:113], v[16:17], v[70:71], v[112:113]
	v_pk_mul_f32 v[108:109], v[36:37], s[52:53] op_sel_hi:[1,0]
	v_pk_mul_f32 v[114:115], v[110:111], s[52:53] op_sel_hi:[1,0]
	v_exp_f32_e32 v108, v108
	v_exp_f32_e32 v114, v114
	v_exp_f32_e32 v109, v109
	v_exp_f32_e32 v115, v115
	v_pk_add_f32 v[108:109], v[108:109], 1.0 op_sel_hi:[1,0]
	v_pk_add_f32 v[114:115], v[114:115], 1.0 op_sel_hi:[1,0]
	v_rcp_f32_e32 v108, v108
	v_rcp_f32_e32 v114, v114
	v_rcp_f32_e32 v109, v109
	v_rcp_f32_e32 v115, v115
	v_pk_mul_f32 v[36:37], v[36:37], v[108:109]
	v_pk_mul_f32 v[110:111], v[110:111], v[114:115]
	v_pk_mul_f32 v[36:37], v[106:107], v[36:37]
	v_pk_mul_f32 v[110:111], v[112:113], v[110:111]
	v_cvt_pk_bf16_f32 v36, v36, v37
	v_cvt_pk_bf16_f32 v110, v110, v111
	global_store_dword v[20:21], v36, off
	v_lshl_add_u64 v[20:21], v[20:21], 0, s[38:39]
	global_store_dword v[20:21], v110, off
	v_lshl_add_u64 v[20:21], v[20:21], 0, s[38:39]
	ds_read2_b64 v[32:35], v117 offset0:192 offset1:208
	v_add_u32_e32 v117, 0x800, v117
	ds_read2_b64 v[56:59], v117 offset0:0 offset1:16
	s_waitcnt lgkmcnt(3)
	v_pk_fma_f32 v[36:37], v[8:9], v[68:69], v[6:7]
	v_pk_fma_f32 v[110:111], v[8:9], v[72:73], v[6:7]
	v_pk_fma_f32 v[106:107], v[14:15], v[70:71], v[18:19]
	v_pk_fma_f32 v[112:113], v[14:15], v[74:75], v[18:19]
	v_pk_fma_f32 v[36:37], v[4:5], v[64:65], v[36:37]
	v_pk_fma_f32 v[110:111], v[4:5], v[68:69], v[110:111]
	v_pk_fma_f32 v[106:107], v[12:13], v[66:67], v[106:107]
	v_pk_fma_f32 v[112:113], v[12:13], v[70:71], v[112:113]
	v_pk_fma_f32 v[36:37], v[10:11], v[72:73], v[36:37]
	v_pk_fma_f32 v[110:111], v[10:11], v[76:77], v[110:111]
	v_pk_fma_f32 v[106:107], v[16:17], v[74:75], v[106:107]
	v_pk_fma_f32 v[112:113], v[16:17], v[78:79], v[112:113]
	v_pk_mul_f32 v[108:109], v[36:37], s[52:53] op_sel_hi:[1,0]
	v_pk_mul_f32 v[114:115], v[110:111], s[52:53] op_sel_hi:[1,0]
	v_exp_f32_e32 v108, v108
	v_exp_f32_e32 v114, v114
	v_exp_f32_e32 v109, v109
	v_exp_f32_e32 v115, v115
	v_pk_add_f32 v[108:109], v[108:109], 1.0 op_sel_hi:[1,0]
	v_pk_add_f32 v[114:115], v[114:115], 1.0 op_sel_hi:[1,0]
	v_rcp_f32_e32 v108, v108
	v_rcp_f32_e32 v114, v114
	v_rcp_f32_e32 v109, v109
	v_rcp_f32_e32 v115, v115
	v_pk_mul_f32 v[36:37], v[36:37], v[108:109]
	v_pk_mul_f32 v[110:111], v[110:111], v[114:115]
	v_pk_mul_f32 v[36:37], v[106:107], v[36:37]
	v_pk_mul_f32 v[110:111], v[112:113], v[110:111]
	v_cvt_pk_bf16_f32 v36, v36, v37
	v_cvt_pk_bf16_f32 v110, v110, v111
	global_store_dword v[20:21], v36, off
	v_lshl_add_u64 v[20:21], v[20:21], 0, s[38:39]
	global_store_dword v[20:21], v110, off
	v_lshl_add_u64 v[20:21], v[20:21], 0, s[38:39]
	ds_read2_b64 v[60:63], v117 offset0:64 offset1:80
	ds_read2_b64 v[64:67], v117 offset0:128 offset1:144
	s_waitcnt lgkmcnt(3)
	v_pk_fma_f32 v[36:37], v[8:9], v[76:77], v[6:7]
	v_pk_fma_f32 v[110:111], v[8:9], v[102:103], v[6:7]
	v_pk_fma_f32 v[106:107], v[14:15], v[78:79], v[18:19]
	v_pk_fma_f32 v[112:113], v[14:15], v[104:105], v[18:19]
	v_pk_fma_f32 v[36:37], v[4:5], v[72:73], v[36:37]
	v_pk_fma_f32 v[110:111], v[4:5], v[76:77], v[110:111]
	v_pk_fma_f32 v[106:107], v[12:13], v[74:75], v[106:107]
	v_pk_fma_f32 v[112:113], v[12:13], v[78:79], v[112:113]
	v_pk_fma_f32 v[36:37], v[10:11], v[102:103], v[36:37]
	v_pk_fma_f32 v[110:111], v[10:11], v[32:33], v[110:111]
	v_pk_fma_f32 v[106:107], v[16:17], v[104:105], v[106:107]
	v_pk_fma_f32 v[112:113], v[16:17], v[34:35], v[112:113]
	v_pk_mul_f32 v[108:109], v[36:37], s[52:53] op_sel_hi:[1,0]
	v_pk_mul_f32 v[114:115], v[110:111], s[52:53] op_sel_hi:[1,0]
	v_exp_f32_e32 v108, v108
	v_exp_f32_e32 v114, v114
	v_exp_f32_e32 v109, v109
	v_exp_f32_e32 v115, v115
	v_pk_add_f32 v[108:109], v[108:109], 1.0 op_sel_hi:[1,0]
	v_pk_add_f32 v[114:115], v[114:115], 1.0 op_sel_hi:[1,0]
	v_rcp_f32_e32 v108, v108
	v_rcp_f32_e32 v114, v114
	v_rcp_f32_e32 v109, v109
	v_rcp_f32_e32 v115, v115
	v_pk_mul_f32 v[36:37], v[36:37], v[108:109]
	v_pk_mul_f32 v[110:111], v[110:111], v[114:115]
	v_pk_mul_f32 v[36:37], v[106:107], v[36:37]
	v_pk_mul_f32 v[110:111], v[112:113], v[110:111]
	v_cvt_pk_bf16_f32 v36, v36, v37
	v_cvt_pk_bf16_f32 v110, v110, v111
	global_store_dword v[20:21], v36, off
	v_lshl_add_u64 v[20:21], v[20:21], 0, s[38:39]
	global_store_dword v[20:21], v110, off
	v_lshl_add_u64 v[20:21], v[20:21], 0, s[38:39]
	ds_read2_b64 v[68:71], v117 offset0:192 offset1:208
	v_add_u32_e32 v117, 0x800, v117
	ds_read2_b64 v[72:75], v117 offset0:0 offset1:16
	s_waitcnt lgkmcnt(3)
	v_pk_fma_f32 v[36:37], v[8:9], v[32:33], v[6:7]
	v_pk_fma_f32 v[110:111], v[8:9], v[56:57], v[6:7]
	v_pk_fma_f32 v[106:107], v[14:15], v[34:35], v[18:19]
	v_pk_fma_f32 v[112:113], v[14:15], v[58:59], v[18:19]
	v_pk_fma_f32 v[36:37], v[4:5], v[102:103], v[36:37]
	v_pk_fma_f32 v[110:111], v[4:5], v[32:33], v[110:111]
	v_pk_fma_f32 v[106:107], v[12:13], v[104:105], v[106:107]
	v_pk_fma_f32 v[112:113], v[12:13], v[34:35], v[112:113]
	v_pk_fma_f32 v[36:37], v[10:11], v[56:57], v[36:37]
	v_pk_fma_f32 v[110:111], v[10:11], v[60:61], v[110:111]
	v_pk_fma_f32 v[106:107], v[16:17], v[58:59], v[106:107]
	v_pk_fma_f32 v[112:113], v[16:17], v[62:63], v[112:113]
	v_pk_mul_f32 v[108:109], v[36:37], s[52:53] op_sel_hi:[1,0]
	v_pk_mul_f32 v[114:115], v[110:111], s[52:53] op_sel_hi:[1,0]
	v_exp_f32_e32 v108, v108
	v_exp_f32_e32 v114, v114
	v_exp_f32_e32 v109, v109
	v_exp_f32_e32 v115, v115
	v_pk_add_f32 v[108:109], v[108:109], 1.0 op_sel_hi:[1,0]
	v_pk_add_f32 v[114:115], v[114:115], 1.0 op_sel_hi:[1,0]
	v_rcp_f32_e32 v108, v108
	v_rcp_f32_e32 v114, v114
	v_rcp_f32_e32 v109, v109
	v_rcp_f32_e32 v115, v115
	v_pk_mul_f32 v[36:37], v[36:37], v[108:109]
	v_pk_mul_f32 v[110:111], v[110:111], v[114:115]
	v_pk_mul_f32 v[36:37], v[106:107], v[36:37]
	v_pk_mul_f32 v[110:111], v[112:113], v[110:111]
	v_cvt_pk_bf16_f32 v36, v36, v37
	v_cvt_pk_bf16_f32 v110, v110, v111
	global_store_dword v[20:21], v36, off
	v_lshl_add_u64 v[20:21], v[20:21], 0, s[38:39]
	global_store_dword v[20:21], v110, off
	v_lshl_add_u64 v[20:21], v[20:21], 0, s[38:39]
	ds_read2_b64 v[76:79], v117 offset0:64 offset1:80
	ds_read2_b64 v[102:105], v117 offset0:128 offset1:144
	s_waitcnt lgkmcnt(3)
	v_pk_fma_f32 v[36:37], v[8:9], v[60:61], v[6:7]
	v_pk_fma_f32 v[110:111], v[8:9], v[64:65], v[6:7]
	v_pk_fma_f32 v[106:107], v[14:15], v[62:63], v[18:19]
	v_pk_fma_f32 v[112:113], v[14:15], v[66:67], v[18:19]
	v_pk_fma_f32 v[36:37], v[4:5], v[56:57], v[36:37]
	v_pk_fma_f32 v[110:111], v[4:5], v[60:61], v[110:111]
	v_pk_fma_f32 v[106:107], v[12:13], v[58:59], v[106:107]
	v_pk_fma_f32 v[112:113], v[12:13], v[62:63], v[112:113]
	v_pk_fma_f32 v[36:37], v[10:11], v[64:65], v[36:37]
	v_pk_fma_f32 v[110:111], v[10:11], v[68:69], v[110:111]
	v_pk_fma_f32 v[106:107], v[16:17], v[66:67], v[106:107]
	v_pk_fma_f32 v[112:113], v[16:17], v[70:71], v[112:113]
	v_pk_mul_f32 v[108:109], v[36:37], s[52:53] op_sel_hi:[1,0]
	v_pk_mul_f32 v[114:115], v[110:111], s[52:53] op_sel_hi:[1,0]
	v_exp_f32_e32 v108, v108
	v_exp_f32_e32 v114, v114
	v_exp_f32_e32 v109, v109
	v_exp_f32_e32 v115, v115
	v_pk_add_f32 v[108:109], v[108:109], 1.0 op_sel_hi:[1,0]
	v_pk_add_f32 v[114:115], v[114:115], 1.0 op_sel_hi:[1,0]
	v_rcp_f32_e32 v108, v108
	v_rcp_f32_e32 v114, v114
	v_rcp_f32_e32 v109, v109
	v_rcp_f32_e32 v115, v115
	v_pk_mul_f32 v[36:37], v[36:37], v[108:109]
	v_pk_mul_f32 v[110:111], v[110:111], v[114:115]
	v_pk_mul_f32 v[36:37], v[106:107], v[36:37]
	v_pk_mul_f32 v[110:111], v[112:113], v[110:111]
	v_cvt_pk_bf16_f32 v36, v36, v37
	v_cvt_pk_bf16_f32 v110, v110, v111
	global_store_dword v[20:21], v36, off
	v_lshl_add_u64 v[20:21], v[20:21], 0, s[38:39]
	global_store_dword v[20:21], v110, off
	v_lshl_add_u64 v[20:21], v[20:21], 0, s[38:39]
	ds_read2_b64 v[32:35], v117 offset0:192 offset1:208
	s_waitcnt lgkmcnt(2)
	v_pk_fma_f32 v[36:37], v[8:9], v[68:69], v[6:7]
	v_pk_fma_f32 v[110:111], v[8:9], v[72:73], v[6:7]
	v_pk_fma_f32 v[106:107], v[14:15], v[70:71], v[18:19]
	v_pk_fma_f32 v[112:113], v[14:15], v[74:75], v[18:19]
	v_pk_fma_f32 v[36:37], v[4:5], v[64:65], v[36:37]
	v_pk_fma_f32 v[110:111], v[4:5], v[68:69], v[110:111]
	v_pk_fma_f32 v[106:107], v[12:13], v[66:67], v[106:107]
	v_pk_fma_f32 v[112:113], v[12:13], v[70:71], v[112:113]
	v_pk_fma_f32 v[36:37], v[10:11], v[72:73], v[36:37]
	v_pk_fma_f32 v[110:111], v[10:11], v[76:77], v[110:111]
	v_pk_fma_f32 v[106:107], v[16:17], v[74:75], v[106:107]
	v_pk_fma_f32 v[112:113], v[16:17], v[78:79], v[112:113]
	v_pk_mul_f32 v[108:109], v[36:37], s[52:53] op_sel_hi:[1,0]
	v_pk_mul_f32 v[114:115], v[110:111], s[52:53] op_sel_hi:[1,0]
	v_exp_f32_e32 v108, v108
	v_exp_f32_e32 v114, v114
	v_exp_f32_e32 v109, v109
	v_exp_f32_e32 v115, v115
	v_pk_add_f32 v[108:109], v[108:109], 1.0 op_sel_hi:[1,0]
	v_pk_add_f32 v[114:115], v[114:115], 1.0 op_sel_hi:[1,0]
	v_rcp_f32_e32 v108, v108
	v_rcp_f32_e32 v114, v114
	v_rcp_f32_e32 v109, v109
	v_rcp_f32_e32 v115, v115
	v_pk_mul_f32 v[36:37], v[36:37], v[108:109]
	v_pk_mul_f32 v[110:111], v[110:111], v[114:115]
	v_pk_mul_f32 v[36:37], v[106:107], v[36:37]
	v_pk_mul_f32 v[110:111], v[112:113], v[110:111]
	v_cvt_pk_bf16_f32 v36, v36, v37
	v_cvt_pk_bf16_f32 v110, v110, v111
	global_store_dword v[20:21], v36, off
	v_lshl_add_u64 v[20:21], v[20:21], 0, s[38:39]
	global_store_dword v[20:21], v110, off
	v_lshl_add_u64 v[20:21], v[20:21], 0, s[38:39]
	s_waitcnt lgkmcnt(0)
	v_pk_fma_f32 v[36:37], v[8:9], v[76:77], v[6:7]
	v_pk_fma_f32 v[110:111], v[8:9], v[102:103], v[6:7]
	v_pk_fma_f32 v[106:107], v[14:15], v[78:79], v[18:19]
	v_pk_fma_f32 v[112:113], v[14:15], v[104:105], v[18:19]
	v_pk_fma_f32 v[36:37], v[4:5], v[72:73], v[36:37]
	v_pk_fma_f32 v[110:111], v[4:5], v[76:77], v[110:111]
	v_pk_fma_f32 v[106:107], v[12:13], v[74:75], v[106:107]
	v_pk_fma_f32 v[112:113], v[12:13], v[78:79], v[112:113]
	v_pk_fma_f32 v[36:37], v[10:11], v[102:103], v[36:37]
	v_pk_fma_f32 v[110:111], v[10:11], v[32:33], v[110:111]
	v_pk_fma_f32 v[106:107], v[16:17], v[104:105], v[106:107]
	v_pk_fma_f32 v[112:113], v[16:17], v[34:35], v[112:113]
	v_pk_mul_f32 v[108:109], v[36:37], s[52:53] op_sel_hi:[1,0]
	v_pk_mul_f32 v[114:115], v[110:111], s[52:53] op_sel_hi:[1,0]
	v_exp_f32_e32 v108, v108
	v_exp_f32_e32 v114, v114
	v_exp_f32_e32 v109, v109
	v_exp_f32_e32 v115, v115
	v_pk_add_f32 v[108:109], v[108:109], 1.0 op_sel_hi:[1,0]
	v_pk_add_f32 v[114:115], v[114:115], 1.0 op_sel_hi:[1,0]
	v_rcp_f32_e32 v108, v108
	v_rcp_f32_e32 v114, v114
	v_rcp_f32_e32 v109, v109
	v_rcp_f32_e32 v115, v115
	v_pk_mul_f32 v[36:37], v[36:37], v[108:109]
	v_pk_mul_f32 v[110:111], v[110:111], v[114:115]
	v_pk_mul_f32 v[36:37], v[106:107], v[36:37]
	v_pk_mul_f32 v[110:111], v[112:113], v[110:111]
	v_cvt_pk_bf16_f32 v36, v36, v37
	v_cvt_pk_bf16_f32 v110, v110, v111
	global_store_dword v[20:21], v36, off
	v_lshl_add_u64 v[20:21], v[20:21], 0, s[38:39]
	s_and_saveexec_b64 s[2:3], vcc
	global_store_dword v[20:21], v110, off
	s_or_b64 exec, exec, s[2:3]
	s_branch .LBB0_1066
